# attention row-sum via v_pk_add + dropped canonical v_max, with 4-byte pad so code shifts are multiples of 8 bytes; + no entry grid.sync
# speedup vs baseline: 1.0197x; 1.0134x over previous
.LBB0_217:
	v_add_u32_e32 v170, s41, v240
	ds_read_b64_tr_b16 v[166:167], v170 offset:24576
	ds_read_b64_tr_b16 v[168:169], v170 offset:25088
	s_waitcnt lgkmcnt(9)
	v_mfma_f32_32x32x16_bf16 v[32:47], v[158:161], v[110:113], v[32:47]
	v_cvt_pk_bf16_f32 v126, v80, v81
	v_cvt_pk_bf16_f32 v127, v82, v83
	v_pk_add_f32 v[80:81], v[80:81], v[82:83]
	v_pk_add_f32 v[80:81], v[80:81], v[84:85]
	ds_read_b64_tr_b16 v[162:163], v170 offset:28672
	ds_read_b64_tr_b16 v[164:165], v170 offset:29184
	s_waitcnt lgkmcnt(10)
	v_mfma_f32_32x32x16_bf16 v[48:63], v[150:153], v[110:113], v[48:63]
	v_pk_add_f32 v[80:81], v[80:81], v[86:87]
	v_pk_add_f32 v[80:81], v[80:81], v[88:89]
	v_cvt_pk_bf16_f32 v128, v84, v85
	v_cvt_pk_bf16_f32 v129, v86, v87
	ds_read_b64_tr_b16 v[158:159], v170 offset:25600
	ds_read_b64_tr_b16 v[160:161], v170 offset:26112
	s_waitcnt lgkmcnt(11)
	v_mfma_f32_32x32x16_bf16 v[32:47], v[154:157], v[106:109], v[32:47]
	v_pk_add_f32 v[80:81], v[80:81], v[90:91]
	v_pk_add_f32 v[80:81], v[80:81], v[92:93]
	v_cvt_pk_bf16_f32 v122, v88, v89
	v_cvt_pk_bf16_f32 v123, v90, v91
	ds_read_b64_tr_b16 v[154:155], v170 offset:29696
	ds_read_b64_tr_b16 v[156:157], v170 offset:30208
	s_waitcnt lgkmcnt(12)
	v_mfma_f32_32x32x16_bf16 v[48:63], v[142:145], v[106:109], v[48:63]
	v_pk_add_f32 v[80:81], v[80:81], v[94:95]
	v_pk_add_f32 v[80:81], v[80:81], v[64:65]
	v_cvt_pk_bf16_f32 v124, v92, v93
	v_cvt_pk_bf16_f32 v125, v94, v95
	ds_read_b64_tr_b16 v[150:151], v170 offset:26624
	ds_read_b64_tr_b16 v[152:153], v170 offset:27136
	s_waitcnt lgkmcnt(13)
	v_mfma_f32_32x32x16_bf16 v[32:47], v[146:149], v[102:105], v[32:47]
	v_pk_add_f32 v[80:81], v[80:81], v[66:67]
	v_pk_add_f32 v[80:81], v[80:81], v[68:69]
	v_cvt_pk_bf16_f32 v118, v64, v65
	v_cvt_pk_bf16_f32 v119, v66, v67
	ds_read_b64_tr_b16 v[146:147], v170 offset:30720
	ds_read_b64_tr_b16 v[148:149], v170 offset:31232
	s_waitcnt lgkmcnt(14)
	v_mfma_f32_32x32x16_bf16 v[48:63], v[134:137], v[102:105], v[48:63]
	v_pk_add_f32 v[80:81], v[80:81], v[70:71]
	v_pk_add_f32 v[80:81], v[80:81], v[72:73]
	v_cvt_pk_bf16_f32 v120, v68, v69
	v_cvt_pk_bf16_f32 v121, v70, v71
	ds_read_b64_tr_b16 v[142:143], v170 offset:27648
	ds_read_b64_tr_b16 v[144:145], v170 offset:28160
	s_waitcnt lgkmcnt(14)
	v_mfma_f32_32x32x16_bf16 v[32:47], v[138:141], v[98:101], v[32:47]
	v_pk_add_f32 v[80:81], v[80:81], v[74:75]
	v_pk_add_f32 v[80:81], v[80:81], v[76:77]
	v_cvt_pk_bf16_f32 v114, v72, v73
	v_cvt_pk_bf16_f32 v115, v74, v75
	ds_read_b64_tr_b16 v[134:135], v170 offset:31744
	ds_read_b64_tr_b16 v[136:137], v170 offset:32256
	v_mfma_f32_32x32x16_bf16 v[48:63], v[130:133], v[98:101], v[48:63]
	v_pk_add_f32 v[80:81], v[80:81], v[78:79]
	v_add_f32_e32 v66, v80, v81
	s_nop 0
	v_cvt_pk_bf16_f32 v116, v76, v77
	v_cvt_pk_bf16_f32 v117, v78, v79
	v_lshl_add_u64 v[64:65], v[184:185], 0, s[84:85]
	s_add_i32 s6, s36, s0
	s_mov_b32 s21, m0
	s_mov_b32 m0, s6
	s_nop 0
	global_load_lds_dwordx4 v[64:65], off
	s_mov_b32 m0, s21
	v_lshl_add_u64 v[64:65], v[182:183], 0, s[84:85]
	s_add_i32 s6, s31, s16
	s_mov_b32 s21, m0
	s_mov_b32 m0, s6
	s_nop 0
	global_load_lds_dwordx4 v[64:65], off
	s_mov_b32 m0, s21
	v_max_f32_e32 v64, v32, v33
	v_max3_f32 v65, v34, v35, v49
	v_max3_f32 v64, v64, v48, v50
	v_max3_f32 v64, v64, v51, v36
	v_max3_f32 v65, v65, v38, v39
	v_max3_f32 v64, v64, v37, v52
	v_max3_f32 v65, v65, v54, v55
	v_max3_f32 v64, v64, v53, v40
	v_max3_f32 v65, v65, v42, v43
	v_max3_f32 v64, v64, v41, v56
	v_max3_f32 v65, v65, v58, v59
	v_max3_f32 v64, v64, v57, v44
	v_max3_f32 v65, v65, v46, v47
	v_max3_f32 v64, v64, v45, v60
	v_max3_f32 v65, v65, v62, v63
	v_max3_f32 v64, v64, v61, v65
	v_mov_b32_e32 v65, v64
	s_nop 1
	v_permlane32_swap_b32_e32 v64, v65
	v_max_f32_e32 v64, v64, v65
	v_cmp_lt_f32_e32 vcc, s95, v64
	s_cmp_lg_u64 vcc, 0
	v_add_f32_e32 v187, v241, v66
	s_cselect_b64 s[52:53], -1, 0
	s_cbranch_vccnz .LBB0_225
